# also rebalanced LDS-DMA staging 4+4 per sub-phase in the out-proj/FF2 (EpiRes) GEMM K-loop, same scheme as FF1
# speedup vs baseline: 1.0057x; 1.0032x over previous
.LBB0_223:
	v_mov_b32_e32 v131, v1
	s_cmpk_lt_u32 s28, 0x100
	v_lshl_add_u64 v[14:15], s[40:41], 0, v[0:1]
	v_lshl_add_u64 v[16:17], s[40:41], 0, v[130:131]
	s_cselect_b64 s[40:41], -1, 0
	v_bfe_u32 v145, v8, 4, 2
	s_lshr_b32 s28, s43, 26
	v_and_b32_e32 v144, 15, v8
	s_add_i32 s28, s42, s28
	v_lshlrev_b32_e32 v9, 4, v145
	v_lshlrev_b32_e32 v8, 2, v8
	s_and_b32 s60, s44, 3
	s_ashr_i32 s61, s28, 6
	v_lshl_or_b32 v9, v144, 6, v9
	s_lshl_b32 s28, s29, 13
	v_and_b32_e32 v8, 32, v8
	v_lshl_add_u64 v[10:11], s[58:59], 0, v[0:1]
	v_bitop3_b32 v22, v9, s28, v8 bitop3:0xde
	s_lshl_b32 s28, s60, 12
	v_lshl_add_u64 v[12:13], s[58:59], 0, v[130:131]
	v_mov_b32_e32 v135, v1
	v_bitop3_b32 v146, v9, s28, v8 bitop3:0xde
	s_add_i32 m0, s27, 0x18000
	v_lshl_add_u64 v[8:9], v[10:11], 0, s[24:25]
	v_lshl_add_u64 v[18:19], s[56:57], 0, v[134:135]
	v_mov_b32_e32 v133, v1
	s_waitcnt vmcnt(2)
	s_barrier
	global_load_lds_dwordx4 v[8:9], off
	v_lshl_add_u64 v[8:9], v[12:13], 0, s[24:25]
	s_add_i32 m0, s27, 0x1a000
	s_add_i32 s64, s27, 0x8000
	v_lshl_add_u64 v[20:21], s[56:57], 0, v[132:133]
	global_load_lds_dwordx4 v[8:9], off
	s_add_i32 s65, s27, 0xa000
	s_lshl_b32 s62, s29, 6
	s_add_i32 m0, s27, 0x1c000
	v_lshl_add_u64 v[8:9], v[14:15], 0, s[24:25]
	global_load_lds_dwordx4 v[8:9], off
	v_lshl_add_u64 v[8:9], v[16:17], 0, s[24:25]
	s_add_i32 m0, s27, 0x1e000
	s_lshl_b32 s63, s60, 5
	global_load_lds_dwordx4 v[8:9], off
	s_waitcnt vmcnt(4)
	v_add_u32_e32 v5, v7, v5
	v_add_u32_e32 v2, v4, v2
	s_cmp_gt_i32 s42, 63
	v_add_lshl_u32 v6, v5, v6, 1
	v_mov_b32_e32 v7, v1
	v_add_lshl_u32 v2, v2, v3, 1
	v_mov_b32_e32 v3, v1
	v_readlane_b32 s28, v236, 24
	s_cselect_b64 s[42:43], -1, 0
	s_add_i32 s66, s61, -2
	v_lshl_add_u64 v[136:137], s[2:3], 0, v[6:7]
	v_lshl_add_u64 v[138:139], s[2:3], 0, v[2:3]
	s_mov_b32 s67, 0
	v_add_u32_e32 v147, 0, v22
	v_readlane_b32 s29, v236, 25
	s_mov_b64 s[44:45], s[58:59]
	s_barrier
	s_branch .LBB0_226

.LBB0_230:
	s_add_i32 s74, s58, 2
	s_add_u32 s75, s56, 0x80
	s_addc_u32 s59, s57, 0
	s_add_i32 s78, 0, 0x10000
	s_cmp_eq_u32 s66, s58
	s_cselect_b32 s59, s29, s59
	s_cselect_b32 s58, s50, s75
	s_cselect_b32 s81, s45, s55
	s_cselect_b32 s80, s44, s51
	s_add_i32 s75, 0, 0x14000
	v_add_u32_e32 v156, s78, v146
	v_add_u32_e32 v172, s75, v146
	ds_read_b128 v[140:143], v156
	ds_read_b128 v[148:151], v156 offset:1024
	ds_read_b128 v[152:155], v156 offset:2048
	ds_read_b128 v[156:159], v156 offset:3072
	ds_read_b128 v[160:163], v172
	ds_read_b128 v[164:167], v172 offset:1024
	ds_read_b128 v[168:171], v172 offset:2048
	ds_read_b128 v[172:175], v172 offset:3072
	v_lshl_add_u64 v[188:189], s[56:57], 0, v[134:135]
	s_mov_b32 m0, s64
	ds_read_b128 v[176:179], v147
	ds_read_b128 v[180:183], v147 offset:1024
	ds_read_b128 v[184:187], v147 offset:2048
	ds_read_b128 v[200:203], v147 offset:3072
	ds_read_b128 v[204:207], v147 offset:4096
	ds_read_b128 v[208:211], v147 offset:5120
	ds_read_b128 v[212:215], v147 offset:6144
	ds_read_b128 v[216:219], v147 offset:7168
	global_load_lds_dwordx4 v[188:189], off
	v_lshl_add_u64 v[188:189], s[56:57], 0, v[132:133]
	s_mov_b32 m0, s65
	s_nop 0
	global_load_lds_dwordx4 v[188:189], off
	v_lshl_add_u64 v[188:189], s[56:57], 0, v[136:137]
	s_add_i32 m0, s27, 0xc000
	s_nop 0
	global_load_lds_dwordx4 v[188:189], off
	v_lshl_add_u64 v[188:189], s[56:57], 0, v[138:139]
	s_add_i32 m0, s27, 0xe000
	s_nop 0
	global_load_lds_dwordx4 v[188:189], off
	s_waitcnt vmcnt(8)
	s_waitcnt lgkmcnt(0)
	s_barrier
	s_setprio 1
	s_waitcnt lgkmcnt(0)
	v_mfma_f32_16x16x32_bf16 v[122:125], v[140:143], v[176:179], v[122:125]
	v_mfma_f32_16x16x32_bf16 v[126:129], v[152:155], v[176:179], v[126:129]
	v_mfma_f32_16x16x32_bf16 v[110:113], v[140:143], v[184:187], v[110:113]
	v_mfma_f32_16x16x32_bf16 v[106:109], v[152:155], v[184:187], v[106:109]
	v_mfma_f32_16x16x32_bf16 v[94:97], v[140:143], v[204:207], v[94:97]
	v_mfma_f32_16x16x32_bf16 v[90:93], v[152:155], v[204:207], v[90:93]
	v_mfma_f32_16x16x32_bf16 v[78:81], v[140:143], v[212:215], v[78:81]
	v_mfma_f32_16x16x32_bf16 v[74:77], v[152:155], v[212:215], v[74:77]
	v_mfma_f32_16x16x32_bf16 v[122:125], v[148:151], v[180:183], v[122:125]
	v_mfma_f32_16x16x32_bf16 v[126:129], v[156:159], v[180:183], v[126:129]
	v_mfma_f32_16x16x32_bf16 v[110:113], v[148:151], v[200:203], v[110:113]
	v_mfma_f32_16x16x32_bf16 v[106:109], v[156:159], v[200:203], v[106:109]
	v_mfma_f32_16x16x32_bf16 v[94:97], v[148:151], v[208:211], v[94:97]
	v_mfma_f32_16x16x32_bf16 v[90:93], v[156:159], v[208:211], v[90:93]
	v_mfma_f32_16x16x32_bf16 v[78:81], v[148:151], v[216:219], v[78:81]
	v_mfma_f32_16x16x32_bf16 v[74:77], v[156:159], v[216:219], v[74:77]
	s_setprio 0
	s_setprio 1
	v_mfma_f32_16x16x32_bf16 v[118:121], v[160:163], v[176:179], v[118:121]
	v_mfma_f32_16x16x32_bf16 v[114:117], v[168:171], v[176:179], v[114:117]
	v_mfma_f32_16x16x32_bf16 v[102:105], v[160:163], v[184:187], v[102:105]
	v_mfma_f32_16x16x32_bf16 v[98:101], v[168:171], v[184:187], v[98:101]
	v_mfma_f32_16x16x32_bf16 v[86:89], v[160:163], v[204:207], v[86:89]
	v_mfma_f32_16x16x32_bf16 v[82:85], v[168:171], v[204:207], v[82:85]
	v_mfma_f32_16x16x32_bf16 v[70:73], v[160:163], v[212:215], v[70:73]
	v_mfma_f32_16x16x32_bf16 v[66:69], v[168:171], v[212:215], v[66:69]
	v_mfma_f32_16x16x32_bf16 v[118:121], v[164:167], v[180:183], v[118:121]
	v_mfma_f32_16x16x32_bf16 v[114:117], v[172:175], v[180:183], v[114:117]
	v_mfma_f32_16x16x32_bf16 v[102:105], v[164:167], v[200:203], v[102:105]
	v_mfma_f32_16x16x32_bf16 v[98:101], v[172:175], v[200:203], v[98:101]
	v_mfma_f32_16x16x32_bf16 v[86:89], v[164:167], v[208:211], v[86:89]
	v_mfma_f32_16x16x32_bf16 v[82:85], v[172:175], v[208:211], v[82:85]
	v_mfma_f32_16x16x32_bf16 v[70:73], v[164:167], v[216:219], v[70:73]
	v_mfma_f32_16x16x32_bf16 v[66:69], v[172:175], v[216:219], v[66:69]
	s_setprio 0
	s_barrier
	s_add_i32 s78, s78, s5
	v_lshl_add_u64 v[188:189], s[80:81], 0, v[0:1]
	s_mov_b32 m0, s78
	ds_read_b128 v[176:179], v147 offset:16384
	ds_read_b128 v[180:183], v147 offset:17408
	ds_read_b128 v[184:187], v147 offset:18432
	ds_read_b128 v[200:203], v147 offset:19456
	ds_read_b128 v[204:207], v147 offset:20480
	ds_read_b128 v[208:211], v147 offset:21504
	ds_read_b128 v[212:215], v147 offset:22528
	ds_read_b128 v[216:219], v147 offset:23552
	global_load_lds_dwordx4 v[188:189], off
	s_add_i32 m0, s78, 0x2000
	v_lshl_add_u64 v[220:221], s[80:81], 0, v[130:131]
	s_add_u32 s80, s80, s6
	s_addc_u32 s81, s81, s7
	s_add_i32 s75, s75, s5
	global_load_lds_dwordx4 v[220:221], off
	v_lshl_add_u64 v[222:223], s[80:81], 0, v[0:1]
	s_mov_b32 m0, s75
	v_lshl_add_u64 v[224:225], s[80:81], 0, v[130:131]
	global_load_lds_dwordx4 v[222:223], off
	s_add_i32 m0, s75, 0x2000
	v_lshl_add_u64 v[226:227], s[58:59], 0, v[134:135]
	global_load_lds_dwordx4 v[224:225], off
	v_lshl_add_u64 v[228:229], s[58:59], 0, v[132:133]
	s_waitcnt vmcnt(6)
	s_waitcnt lgkmcnt(0)
	s_barrier
	s_setprio 1
	s_waitcnt lgkmcnt(0)
	v_mfma_f32_16x16x32_bf16 v[62:65], v[140:143], v[176:179], v[62:65]
	v_mfma_f32_16x16x32_bf16 v[58:61], v[152:155], v[176:179], v[58:61]
	v_mfma_f32_16x16x32_bf16 v[46:49], v[140:143], v[184:187], v[46:49]
	v_mfma_f32_16x16x32_bf16 v[42:45], v[152:155], v[184:187], v[42:45]
	v_mfma_f32_16x16x32_bf16 v[30:33], v[140:143], v[204:207], v[30:33]
	v_mfma_f32_16x16x32_bf16 v[26:29], v[152:155], v[204:207], v[26:29]
	v_mfma_f32_16x16x32_bf16 v[14:17], v[140:143], v[212:215], v[14:17]
	v_mfma_f32_16x16x32_bf16 v[10:13], v[152:155], v[212:215], v[10:13]
	v_mfma_f32_16x16x32_bf16 v[62:65], v[148:151], v[180:183], v[62:65]
	v_mfma_f32_16x16x32_bf16 v[58:61], v[156:159], v[180:183], v[58:61]
	v_mfma_f32_16x16x32_bf16 v[46:49], v[148:151], v[200:203], v[46:49]
	v_mfma_f32_16x16x32_bf16 v[42:45], v[156:159], v[200:203], v[42:45]
	v_mfma_f32_16x16x32_bf16 v[30:33], v[148:151], v[208:211], v[30:33]
	v_mfma_f32_16x16x32_bf16 v[26:29], v[156:159], v[208:211], v[26:29]
	v_mfma_f32_16x16x32_bf16 v[14:17], v[148:151], v[216:219], v[14:17]
	v_mfma_f32_16x16x32_bf16 v[10:13], v[156:159], v[216:219], v[10:13]
	s_setprio 0
	s_setprio 1
	v_mfma_f32_16x16x32_bf16 v[54:57], v[160:163], v[176:179], v[54:57]
	v_mfma_f32_16x16x32_bf16 v[50:53], v[168:171], v[176:179], v[50:53]
	v_mfma_f32_16x16x32_bf16 v[38:41], v[160:163], v[184:187], v[38:41]
	v_mfma_f32_16x16x32_bf16 v[34:37], v[168:171], v[184:187], v[34:37]
	v_mfma_f32_16x16x32_bf16 v[22:25], v[160:163], v[204:207], v[22:25]
	v_mfma_f32_16x16x32_bf16 v[18:21], v[168:171], v[204:207], v[18:21]
	v_mfma_f32_16x16x32_bf16 v[6:9], v[160:163], v[212:215], v[6:9]
	v_mfma_f32_16x16x32_bf16 v[2:5], v[168:171], v[212:215], v[2:5]
	v_mfma_f32_16x16x32_bf16 v[54:57], v[164:167], v[180:183], v[54:57]
	v_mfma_f32_16x16x32_bf16 v[50:53], v[172:175], v[180:183], v[50:53]
	v_mfma_f32_16x16x32_bf16 v[38:41], v[164:167], v[200:203], v[38:41]
	v_mfma_f32_16x16x32_bf16 v[34:37], v[172:175], v[200:203], v[34:37]
	v_mfma_f32_16x16x32_bf16 v[22:25], v[164:167], v[208:211], v[22:25]
	v_mfma_f32_16x16x32_bf16 v[18:21], v[172:175], v[208:211], v[18:21]
	v_mfma_f32_16x16x32_bf16 v[6:9], v[164:167], v[216:219], v[6:9]
	v_mfma_f32_16x16x32_bf16 v[2:5], v[172:175], v[216:219], v[2:5]
	s_setprio 0
	s_barrier
	s_add_i32 s75, 0, 0x18000
	s_add_i32 s78, 0, 0x1c000
	v_add_u32_e32 v156, s75, v146
	v_add_u32_e32 v172, s78, v146
	ds_read_b128 v[140:143], v156
	ds_read_b128 v[148:151], v156 offset:1024
	ds_read_b128 v[152:155], v156 offset:2048
	ds_read_b128 v[156:159], v156 offset:3072
	ds_read_b128 v[160:163], v172
	ds_read_b128 v[164:167], v172 offset:1024
	ds_read_b128 v[168:171], v172 offset:2048
	ds_read_b128 v[172:175], v172 offset:3072
	s_add_u32 s58, s58, s2
	s_addc_u32 s59, s59, s3
	s_mov_b32 m0, s27
	v_lshl_add_u64 v[230:231], s[58:59], 0, v[134:135]
	ds_read_b128 v[176:179], v147 offset:32768
	ds_read_b128 v[180:183], v147 offset:33792
	ds_read_b128 v[184:187], v147 offset:34816
	ds_read_b128 v[200:203], v147 offset:35840
	ds_read_b128 v[204:207], v147 offset:36864
	ds_read_b128 v[208:211], v147 offset:37888
	ds_read_b128 v[212:215], v147 offset:38912
	ds_read_b128 v[216:219], v147 offset:39936
	global_load_lds_dwordx4 v[226:227], off
	s_mov_b32 m0, s30
	s_nop 0
	global_load_lds_dwordx4 v[228:229], off
	s_mov_b32 m0, s31
	s_nop 0
	global_load_lds_dwordx4 v[230:231], off
	v_lshl_add_u64 v[230:231], s[58:59], 0, v[132:133]
	s_mov_b32 m0, s53
	s_nop 0
	global_load_lds_dwordx4 v[230:231], off
	s_waitcnt vmcnt(8)
	s_waitcnt lgkmcnt(0)
	s_barrier
	s_setprio 1
	s_waitcnt lgkmcnt(0)
	v_mfma_f32_16x16x32_bf16 v[122:125], v[140:143], v[176:179], v[122:125]
	v_mfma_f32_16x16x32_bf16 v[126:129], v[152:155], v[176:179], v[126:129]
	v_mfma_f32_16x16x32_bf16 v[110:113], v[140:143], v[184:187], v[110:113]
	v_mfma_f32_16x16x32_bf16 v[106:109], v[152:155], v[184:187], v[106:109]
	v_mfma_f32_16x16x32_bf16 v[94:97], v[140:143], v[204:207], v[94:97]
	v_mfma_f32_16x16x32_bf16 v[90:93], v[152:155], v[204:207], v[90:93]
	v_mfma_f32_16x16x32_bf16 v[78:81], v[140:143], v[212:215], v[78:81]
	v_mfma_f32_16x16x32_bf16 v[74:77], v[152:155], v[212:215], v[74:77]
	v_mfma_f32_16x16x32_bf16 v[122:125], v[148:151], v[180:183], v[122:125]
	v_mfma_f32_16x16x32_bf16 v[126:129], v[156:159], v[180:183], v[126:129]
	v_mfma_f32_16x16x32_bf16 v[110:113], v[148:151], v[200:203], v[110:113]
	v_mfma_f32_16x16x32_bf16 v[106:109], v[156:159], v[200:203], v[106:109]
	v_mfma_f32_16x16x32_bf16 v[94:97], v[148:151], v[208:211], v[94:97]
	v_mfma_f32_16x16x32_bf16 v[90:93], v[156:159], v[208:211], v[90:93]
	v_mfma_f32_16x16x32_bf16 v[78:81], v[148:151], v[216:219], v[78:81]
	v_mfma_f32_16x16x32_bf16 v[74:77], v[156:159], v[216:219], v[74:77]
	s_setprio 0
	s_setprio 1
	v_mfma_f32_16x16x32_bf16 v[118:121], v[160:163], v[176:179], v[118:121]
	v_mfma_f32_16x16x32_bf16 v[114:117], v[168:171], v[176:179], v[114:117]
	v_mfma_f32_16x16x32_bf16 v[102:105], v[160:163], v[184:187], v[102:105]
	v_mfma_f32_16x16x32_bf16 v[98:101], v[168:171], v[184:187], v[98:101]
	v_mfma_f32_16x16x32_bf16 v[86:89], v[160:163], v[204:207], v[86:89]
	v_mfma_f32_16x16x32_bf16 v[82:85], v[168:171], v[204:207], v[82:85]
	v_mfma_f32_16x16x32_bf16 v[70:73], v[160:163], v[212:215], v[70:73]
	v_mfma_f32_16x16x32_bf16 v[66:69], v[168:171], v[212:215], v[66:69]
	v_mfma_f32_16x16x32_bf16 v[118:121], v[164:167], v[180:183], v[118:121]
	v_mfma_f32_16x16x32_bf16 v[114:117], v[172:175], v[180:183], v[114:117]
	v_mfma_f32_16x16x32_bf16 v[102:105], v[164:167], v[200:203], v[102:105]
	v_mfma_f32_16x16x32_bf16 v[98:101], v[172:175], v[200:203], v[98:101]
	v_mfma_f32_16x16x32_bf16 v[86:89], v[164:167], v[208:211], v[86:89]
	v_mfma_f32_16x16x32_bf16 v[82:85], v[172:175], v[208:211], v[82:85]
	v_mfma_f32_16x16x32_bf16 v[70:73], v[164:167], v[216:219], v[70:73]
	v_mfma_f32_16x16x32_bf16 v[66:69], v[172:175], v[216:219], v[66:69]
	s_setprio 0
	s_barrier
	s_add_i32 s58, s75, s5
	v_lshl_add_u64 v[188:189], v[188:189], 0, s[24:25]
	s_mov_b32 m0, s58
	ds_read_b128 v[176:179], v147 offset:49152
	ds_read_b128 v[180:183], v147 offset:50176
	ds_read_b128 v[184:187], v147 offset:51200
	ds_read_b128 v[200:203], v147 offset:52224
	ds_read_b128 v[204:207], v147 offset:53248
	ds_read_b128 v[208:211], v147 offset:54272
	ds_read_b128 v[212:215], v147 offset:55296
	ds_read_b128 v[216:219], v147 offset:56320
	global_load_lds_dwordx4 v[188:189], off
	v_lshl_add_u64 v[188:189], v[220:221], 0, s[24:25]
	s_add_i32 m0, s58, 0x2000
	s_add_i32 s58, s78, s5
	global_load_lds_dwordx4 v[188:189], off
	v_lshl_add_u64 v[188:189], v[222:223], 0, s[24:25]
	s_mov_b32 m0, s58
	s_nop 0
	global_load_lds_dwordx4 v[188:189], off
	v_lshl_add_u64 v[188:189], v[224:225], 0, s[24:25]
	s_add_i32 m0, s58, 0x2000
	s_nop 0
	global_load_lds_dwordx4 v[188:189], off
	s_waitcnt vmcnt(6)
	s_waitcnt lgkmcnt(0)
	s_barrier
	s_setprio 1
	s_waitcnt lgkmcnt(0)
	v_mfma_f32_16x16x32_bf16 v[62:65], v[140:143], v[176:179], v[62:65]
	v_mfma_f32_16x16x32_bf16 v[58:61], v[152:155], v[176:179], v[58:61]
	v_mfma_f32_16x16x32_bf16 v[46:49], v[140:143], v[184:187], v[46:49]
	v_mfma_f32_16x16x32_bf16 v[42:45], v[152:155], v[184:187], v[42:45]
	v_mfma_f32_16x16x32_bf16 v[30:33], v[140:143], v[204:207], v[30:33]
	v_mfma_f32_16x16x32_bf16 v[26:29], v[152:155], v[204:207], v[26:29]
	v_mfma_f32_16x16x32_bf16 v[14:17], v[140:143], v[212:215], v[14:17]
	v_mfma_f32_16x16x32_bf16 v[10:13], v[152:155], v[212:215], v[10:13]
	v_mfma_f32_16x16x32_bf16 v[62:65], v[148:151], v[180:183], v[62:65]
	v_mfma_f32_16x16x32_bf16 v[58:61], v[156:159], v[180:183], v[58:61]
	v_mfma_f32_16x16x32_bf16 v[46:49], v[148:151], v[200:203], v[46:49]
	v_mfma_f32_16x16x32_bf16 v[42:45], v[156:159], v[200:203], v[42:45]
	v_mfma_f32_16x16x32_bf16 v[30:33], v[148:151], v[208:211], v[30:33]
	v_mfma_f32_16x16x32_bf16 v[26:29], v[156:159], v[208:211], v[26:29]
	v_mfma_f32_16x16x32_bf16 v[14:17], v[148:151], v[216:219], v[14:17]
	v_mfma_f32_16x16x32_bf16 v[10:13], v[156:159], v[216:219], v[10:13]
	s_setprio 0
	s_setprio 1
	v_mfma_f32_16x16x32_bf16 v[54:57], v[160:163], v[176:179], v[54:57]
	v_mfma_f32_16x16x32_bf16 v[50:53], v[168:171], v[176:179], v[50:53]
	v_mfma_f32_16x16x32_bf16 v[38:41], v[160:163], v[184:187], v[38:41]
	v_mfma_f32_16x16x32_bf16 v[34:37], v[168:171], v[184:187], v[34:37]
	v_mfma_f32_16x16x32_bf16 v[22:25], v[160:163], v[204:207], v[22:25]
	v_mfma_f32_16x16x32_bf16 v[18:21], v[168:171], v[204:207], v[18:21]
	v_mfma_f32_16x16x32_bf16 v[6:9], v[160:163], v[212:215], v[6:9]
	v_mfma_f32_16x16x32_bf16 v[2:5], v[168:171], v[212:215], v[2:5]
	v_mfma_f32_16x16x32_bf16 v[54:57], v[164:167], v[180:183], v[54:57]
	v_mfma_f32_16x16x32_bf16 v[50:53], v[172:175], v[180:183], v[50:53]
	v_mfma_f32_16x16x32_bf16 v[38:41], v[164:167], v[200:203], v[38:41]
	v_mfma_f32_16x16x32_bf16 v[34:37], v[172:175], v[200:203], v[34:37]
	v_mfma_f32_16x16x32_bf16 v[22:25], v[164:167], v[208:211], v[22:25]
	v_mfma_f32_16x16x32_bf16 v[18:21], v[172:175], v[208:211], v[18:21]
	v_mfma_f32_16x16x32_bf16 v[6:9], v[164:167], v[216:219], v[6:9]
	v_mfma_f32_16x16x32_bf16 v[2:5], v[172:175], v[216:219], v[2:5]
	s_setprio 0
	s_barrier
	s_add_u32 s56, s56, 0x100
	s_addc_u32 s57, s57, 0
	s_add_u32 s51, s51, 0x100
	s_addc_u32 s55, s55, 0
	s_cmp_ge_i32 s74, s61
	s_mov_b32 s58, s74
	s_cbranch_scc0 .LBB0_230
	v_readlane_b32 s74, v236, 30
	v_readlane_b32 s75, v236, 31
	s_mov_b32 s78, s76
